# GLA scan chunk PREP: single vmcnt wait and merged exec-masked write regions (frees SIMD issue slots shared with the GDN wave)
# speedup vs baseline: 1.0041x; 1.0041x over previous
; #define LBAR() do { asm volatile("s_waitcnt lgkmcnt(0)" ::: "memory"); __builtin_amdgcn_s_barrier(); asm volatile("" ::: "memory"); } while (0)
; #define LAS __attribute__((address_space(3)))
; #define GL_LDV(V, j_) do { \
;     V.f0 = L128(bq, (j_) * GL_VB); V.f1 = L128(bq, (j_) * GL_VB + 16); V.k0 = L128(bq, (j_) * GL_VB + 256); V.k1 = L128(bq, (j_) * GL_VB + 272); \
;     V.q0 = L128(bq, (j_) * GL_VB + 512); V.q1 = L128(bq, (j_) * GL_VB + 528); V.vv = L32(bv, (j_) * GL_VB + GL_OFF_V); V.kq = L32(bc, (j_) * GL_VB + GL_OFF_S); } while (0)
; #define GL_PIN(V) asm volatile("" : "+v"(V.f0), "+v"(V.f1), "+v"(V.k0), "+v"(V.k1), "+v"(V.q0), "+v"(V.q1), "+v"(V.vv), "+v"(V.kq), "+v"(S2[0]), "+v"(S2[1]), "+v"(S2[2]), "+v"(S2[3]))
; #define GL_2(jA, jB) GL_LDV(B, jA + 1); __builtin_amdgcn_sched_barrier(0); GL_STEP(A, jA); GL_PIN(B); \
;                      GL_LDV(A, jB + 1); __builtin_amdgcn_sched_barrier(0); GL_STEP(B, jB); GL_PIN(A);
; template <int NW>
; __device__ void scan_gla(const P& p, int l, int b, int h, int dir, int part, LAS char* lds) {
;     ...
;   gl_load<TPW, NCOL>(p, b, ch, vch, lane, dir, 0, wv, R);
;   GL_PREP(0);
;   gl_load<TPW, NCOL>(p, b, ch, vch, lane, dir, 1, wv, R);
;   LBAR();
;   for (int g = 0; g < NCHK; ++g) {
;     LAS char* vbuf = lds + (g & 1) * TC * GL_VB;
;     LAS float* obuf = (LAS float*)(lds + GL_OFF_Y + (g & 1) * TC * NCOL * 4);
;     {
;       GlVec A, B;
;       LAS char* bq = vbuf + dq * 32; LAS char* bv = vbuf + col * 4; LAS char* bc = vbuf;
;       GL_LDV(A, 0); GL_PIN(A);
; #pragma unroll 1
;       for (int s8 = 0; s8 < TC; s8 += 8) {
;         float ykeep = 0.f;
;         GL_2(0, 1) GL_2(2, 3) GL_2(4, 5) GL_2(6, 7)
;         obuf[(s8 + dq) * NCOL + col] = ykeep;
;         bq += 8 * GL_VB; bv += 8 * GL_VB; bc += 8 * GL_VB;
;       }
.LBB0_171:
	v_add_u32_e32 v92, 0x15400, v89
	v_add_u32_e32 v93, 0x15400, v90
	v_add_u32_e32 v94, 0x15400, v88
	ds_read_b32 v121, v94 offset:1808
	ds_read_b32 v120, v93 offset:1680
	ds_read_b128 v[96:99], v92 offset:1440
	ds_read_b128 v[100:103], v92 offset:1424
	ds_read_b128 v[104:107], v92 offset:1184
	ds_read_b128 v[108:111], v92 offset:1168
	ds_read_b128 v[112:115], v92 offset:928
	ds_read_b128 v[116:119], v92 offset:912
	v_pk_mul_f32 v[22:23], v[22:23], v[30:31]
	v_pk_mul_f32 v[4:5], v[4:5], v[32:33]
	v_pk_fma_f32 v[20:21], v[20:21], v[28:29], v[22:23]
	s_nop 0
	v_pk_fma_f32 v[12:13], v[12:13], v[32:33], v[20:21]
	v_pk_fma_f32 v[32:33], v[0:1], v[36:37], v[4:5] op_sel_hi:[1,0,1]
	v_pk_fma_f32 v[12:13], v[14:15], v[34:35], v[12:13]
	v_pk_mul_f32 v[0:1], v[6:7], v[34:35]
	v_pk_mul_f32 v[14:15], v[16:17], v[28:29]
	v_pk_fma_f32 v[34:35], v[2:3], v[36:37], v[0:1] op_sel_hi:[1,0,1]
	v_add_f32_e32 v0, v12, v13
	v_pk_fma_f32 v[28:29], v[8:9], v[36:37], v[14:15] op_sel_hi:[1,0,1]
	v_pk_mul_f32 v[8:9], v[18:19], v[30:31]
	v_add_f32_dpp v0, v0, v0 quad_perm:[1,0,3,2] row_mask:0xf bank_mask:0xf bound_ctrl:1
	v_pk_fma_f32 v[30:31], v[10:11], v[36:37], v[8:9] op_sel_hi:[1,0,1]
	s_nop 0
	v_add_f32_dpp v0, v0, v0 quad_perm:[2,3,0,1] row_mask:0xf bank_mask:0xf bound_ctrl:1
	s_nop 1
	v_add_f32_dpp v0, v0, v0 row_half_mirror row_mask:0xf bank_mask:0xf bound_ctrl:1
	v_fmac_f32_e32 v0, v36, v95
	v_cndmask_b32_e64 v95, 0, v0, s[42:43]
	s_waitcnt lgkmcnt(0)
	ds_read_b32 v122, v94 offset:2720
	ds_read_b32 v36, v93 offset:2592
	ds_read_b128 v[0:3], v92 offset:2352
	ds_read_b128 v[4:7], v92 offset:2336
	ds_read_b128 v[8:11], v92 offset:2096
	ds_read_b128 v[12:15], v92 offset:2080
	ds_read_b128 v[16:19], v92 offset:1840
	ds_read_b128 v[20:23], v92 offset:1824
	v_pk_mul_f32 v[102:103], v[30:31], v[102:103]
	s_nop 0
	v_pk_fma_f32 v[100:101], v[28:29], v[100:101], v[102:103]
	s_nop 0
	v_pk_fma_f32 v[96:97], v[32:33], v[96:97], v[100:101]
	s_nop 0
	v_pk_fma_f32 v[96:97], v[34:35], v[98:99], v[96:97]
	v_pk_mul_f32 v[98:99], v[108:109], v[120:121] op_sel_hi:[1,0]
	s_nop 0
	v_pk_fma_f32 v[116:117], v[28:29], v[116:117], v[98:99]
	v_pk_mul_f32 v[28:29], v[110:111], v[120:121] op_sel_hi:[1,0]
	s_nop 0
	v_pk_fma_f32 v[118:119], v[30:31], v[118:119], v[28:29]
	v_pk_mul_f32 v[28:29], v[104:105], v[120:121] op_sel_hi:[1,0]
	s_nop 0
	v_pk_fma_f32 v[112:113], v[32:33], v[112:113], v[28:29]
	v_pk_mul_f32 v[28:29], v[106:107], v[120:121] op_sel_hi:[1,0]
	s_nop 0
	v_pk_fma_f32 v[114:115], v[34:35], v[114:115], v[28:29]
	v_add_f32_e32 v28, v96, v97
	s_nop 1
	v_add_f32_dpp v28, v28, v28 quad_perm:[1,0,3,2] row_mask:0xf bank_mask:0xf bound_ctrl:1
	s_waitcnt lgkmcnt(0)
	s_nop 0
	v_add_f32_dpp v28, v28, v28 quad_perm:[2,3,0,1] row_mask:0xf bank_mask:0xf bound_ctrl:1
	s_nop 1
	v_add_f32_dpp v28, v28, v28 row_half_mirror row_mask:0xf bank_mask:0xf bound_ctrl:1
	v_fmac_f32_e32 v28, v120, v121
	v_cndmask_b32_e64 v95, v95, v28, s[44:45]
	ds_read_b32 v121, v94 offset:3632
	ds_read_b32 v120, v93 offset:3504
	ds_read_b128 v[28:31], v92 offset:3264
	ds_read_b128 v[32:35], v92 offset:3248
	ds_read_b128 v[96:99], v92 offset:3008
	ds_read_b128 v[100:103], v92 offset:2992
	ds_read_b128 v[104:107], v92 offset:2752
	ds_read_b128 v[108:111], v92 offset:2736
	v_pk_mul_f32 v[6:7], v[118:119], v[6:7]
	s_nop 0
	v_pk_fma_f32 v[4:5], v[116:117], v[4:5], v[6:7]
	s_nop 0
	v_pk_fma_f32 v[0:1], v[112:113], v[0:1], v[4:5]
	s_nop 0
	v_pk_fma_f32 v[0:1], v[114:115], v[2:3], v[0:1]
	v_pk_mul_f32 v[2:3], v[12:13], v[36:37] op_sel_hi:[1,0]
	v_add_f32_e32 v0, v0, v1
	v_pk_fma_f32 v[116:117], v[116:117], v[20:21], v[2:3]
	v_pk_mul_f32 v[2:3], v[14:15], v[36:37] op_sel_hi:[1,0]
	v_add_f32_dpp v0, v0, v0 quad_perm:[1,0,3,2] row_mask:0xf bank_mask:0xf bound_ctrl:1
	v_pk_fma_f32 v[118:119], v[118:119], v[22:23], v[2:3]
	v_pk_mul_f32 v[2:3], v[8:9], v[36:37] op_sel_hi:[1,0]
	v_add_f32_dpp v0, v0, v0 quad_perm:[2,3,0,1] row_mask:0xf bank_mask:0xf bound_ctrl:1
	v_pk_fma_f32 v[112:113], v[112:113], v[16:17], v[2:3]
	v_pk_mul_f32 v[2:3], v[10:11], v[36:37] op_sel_hi:[1,0]
	v_add_f32_dpp v0, v0, v0 row_half_mirror row_mask:0xf bank_mask:0xf bound_ctrl:1
	v_fmac_f32_e32 v0, v36, v122
	v_pk_fma_f32 v[114:115], v[114:115], v[18:19], v[2:3]
	v_cndmask_b32_e64 v95, v95, v0, s[46:47]
	s_waitcnt lgkmcnt(0)
	ds_read_b32 v122, v94 offset:4544
	ds_read_b32 v36, v93 offset:4416
	ds_read_b128 v[0:3], v92 offset:4176
	ds_read_b128 v[4:7], v92 offset:4160
	ds_read_b128 v[8:11], v92 offset:3920
	ds_read_b128 v[12:15], v92 offset:3904
	ds_read_b128 v[16:19], v92 offset:3664
	ds_read_b128 v[20:23], v92 offset:3648
	v_pk_mul_f32 v[34:35], v[118:119], v[34:35]
	s_nop 0
	v_pk_fma_f32 v[32:33], v[116:117], v[32:33], v[34:35]
	s_nop 0
	v_pk_fma_f32 v[28:29], v[112:113], v[28:29], v[32:33]
	s_nop 0
	v_pk_fma_f32 v[28:29], v[114:115], v[30:31], v[28:29]
	v_pk_mul_f32 v[30:31], v[100:101], v[120:121] op_sel_hi:[1,0]
	v_add_f32_e32 v28, v28, v29
	v_pk_fma_f32 v[116:117], v[116:117], v[108:109], v[30:31]
	v_pk_mul_f32 v[30:31], v[102:103], v[120:121] op_sel_hi:[1,0]
	v_add_f32_dpp v28, v28, v28 quad_perm:[1,0,3,2] row_mask:0xf bank_mask:0xf bound_ctrl:1
	v_pk_fma_f32 v[118:119], v[118:119], v[110:111], v[30:31]
	v_pk_mul_f32 v[30:31], v[96:97], v[120:121] op_sel_hi:[1,0]
	v_add_f32_dpp v28, v28, v28 quad_perm:[2,3,0,1] row_mask:0xf bank_mask:0xf bound_ctrl:1
	v_pk_fma_f32 v[112:113], v[112:113], v[104:105], v[30:31]
	v_pk_mul_f32 v[30:31], v[98:99], v[120:121] op_sel_hi:[1,0]
	v_add_f32_dpp v28, v28, v28 row_half_mirror row_mask:0xf bank_mask:0xf bound_ctrl:1
	v_fmac_f32_e32 v28, v120, v121
	v_pk_fma_f32 v[114:115], v[114:115], v[106:107], v[30:31]
	v_cndmask_b32_e64 v95, v95, v28, s[48:49]
	s_waitcnt lgkmcnt(0)
; #define LBAR() do { asm volatile("s_waitcnt lgkmcnt(0)" ::: "memory"); __builtin_amdgcn_s_barrier(); asm volatile("" ::: "memory"); } while (0)
; #define LAS __attribute__((address_space(3)))
; #define GL_LDV(V, j_) do { \
;     V.f0 = L128(bq, (j_) * GL_VB); V.f1 = L128(bq, (j_) * GL_VB + 16); V.k0 = L128(bq, (j_) * GL_VB + 256); V.k1 = L128(bq, (j_) * GL_VB + 272); \
;     V.q0 = L128(bq, (j_) * GL_VB + 512); V.q1 = L128(bq, (j_) * GL_VB + 528); V.vv = L32(bv, (j_) * GL_VB + GL_OFF_V); V.kq = L32(bc, (j_) * GL_VB + GL_OFF_S); } while (0)
; #define GL_PIN(V) asm volatile("" : "+v"(V.f0), "+v"(V.f1), "+v"(V.k0), "+v"(V.k1), "+v"(V.q0), "+v"(V.q1), "+v"(V.vv), "+v"(V.kq), "+v"(S2[0]), "+v"(S2[1]), "+v"(S2[2]), "+v"(S2[3]))
; #define GL_2(jA, jB) GL_LDV(B, jA + 1); __builtin_amdgcn_sched_barrier(0); GL_STEP(A, jA); GL_PIN(B); \
;                      GL_LDV(A, jB + 1); __builtin_amdgcn_sched_barrier(0); GL_STEP(B, jB); GL_PIN(A);
; template <int NW>
; __device__ void scan_gla(const P& p, int l, int b, int h, int dir, int part, LAS char* lds) {
;     ...
;   gl_load<TPW, NCOL>(p, b, ch, vch, lane, dir, 0, wv, R);
;   GL_PREP(0);
;   gl_load<TPW, NCOL>(p, b, ch, vch, lane, dir, 1, wv, R);
;   LBAR();
;   for (int g = 0; g < NCHK; ++g) {
;     LAS char* vbuf = lds + (g & 1) * TC * GL_VB;
;     LAS float* obuf = (LAS float*)(lds + GL_OFF_Y + (g & 1) * TC * NCOL * 4);
;     {
;       GlVec A, B;
;       LAS char* bq = vbuf + dq * 32; LAS char* bv = vbuf + col * 4; LAS char* bc = vbuf;
;       GL_LDV(A, 0); GL_PIN(A);
; #pragma unroll 1
;       for (int s8 = 0; s8 < TC; s8 += 8) {
;         float ykeep = 0.f;
;         GL_2(0, 1) GL_2(2, 3) GL_2(4, 5) GL_2(6, 7)
;         obuf[(s8 + dq) * NCOL + col] = ykeep;
;         bq += 8 * GL_VB; bv += 8 * GL_VB; bc += 8 * GL_VB;
;       }
	ds_read_b32 v121, v94 offset:5456
	ds_read_b32 v120, v93 offset:5328
	ds_read_b128 v[28:31], v92 offset:5088
	ds_read_b128 v[32:35], v92 offset:5072
	ds_read_b128 v[96:99], v92 offset:4832
	ds_read_b128 v[100:103], v92 offset:4816
	ds_read_b128 v[104:107], v92 offset:4576
	ds_read_b128 v[108:111], v92 offset:4560
	v_pk_mul_f32 v[6:7], v[118:119], v[6:7]
	s_nop 0
	v_pk_fma_f32 v[4:5], v[116:117], v[4:5], v[6:7]
	s_nop 0
	v_pk_fma_f32 v[0:1], v[112:113], v[0:1], v[4:5]
	s_nop 0
	v_pk_fma_f32 v[0:1], v[114:115], v[2:3], v[0:1]
	v_pk_mul_f32 v[2:3], v[12:13], v[36:37] op_sel_hi:[1,0]
	v_add_f32_e32 v0, v0, v1
	v_pk_fma_f32 v[116:117], v[116:117], v[20:21], v[2:3]
	v_pk_mul_f32 v[2:3], v[14:15], v[36:37] op_sel_hi:[1,0]
	v_add_f32_dpp v0, v0, v0 quad_perm:[1,0,3,2] row_mask:0xf bank_mask:0xf bound_ctrl:1
	v_pk_fma_f32 v[118:119], v[118:119], v[22:23], v[2:3]
	v_pk_mul_f32 v[2:3], v[8:9], v[36:37] op_sel_hi:[1,0]
	v_add_f32_dpp v0, v0, v0 quad_perm:[2,3,0,1] row_mask:0xf bank_mask:0xf bound_ctrl:1
	v_pk_fma_f32 v[112:113], v[112:113], v[16:17], v[2:3]
	v_pk_mul_f32 v[2:3], v[10:11], v[36:37] op_sel_hi:[1,0]
	v_add_f32_dpp v0, v0, v0 row_half_mirror row_mask:0xf bank_mask:0xf bound_ctrl:1
	v_fmac_f32_e32 v0, v36, v122
	v_pk_fma_f32 v[114:115], v[114:115], v[18:19], v[2:3]
	v_cndmask_b32_e64 v36, v95, v0, s[50:51]
	s_waitcnt lgkmcnt(0)
	ds_read_b32 v123, v94 offset:6368
	ds_read_b32 v122, v93 offset:6240
	ds_read_b128 v[0:3], v92 offset:6000
	ds_read_b128 v[4:7], v92 offset:5984
	ds_read_b128 v[8:11], v92 offset:5744
	ds_read_b128 v[12:15], v92 offset:5728
	ds_read_b128 v[16:19], v92 offset:5488
	ds_read_b128 v[20:23], v92 offset:5472
	v_pk_mul_f32 v[34:35], v[118:119], v[34:35]
	s_nop 0
	v_pk_fma_f32 v[32:33], v[116:117], v[32:33], v[34:35]
	s_nop 0
	v_pk_fma_f32 v[28:29], v[112:113], v[28:29], v[32:33]
	s_nop 0
	v_pk_fma_f32 v[28:29], v[114:115], v[30:31], v[28:29]
	v_pk_mul_f32 v[30:31], v[100:101], v[120:121] op_sel_hi:[1,0]
	v_add_f32_e32 v28, v28, v29
	v_pk_fma_f32 v[116:117], v[116:117], v[108:109], v[30:31]
	v_pk_mul_f32 v[30:31], v[102:103], v[120:121] op_sel_hi:[1,0]
	v_add_f32_dpp v28, v28, v28 quad_perm:[1,0,3,2] row_mask:0xf bank_mask:0xf bound_ctrl:1
	v_pk_fma_f32 v[118:119], v[118:119], v[110:111], v[30:31]
	v_pk_mul_f32 v[30:31], v[96:97], v[120:121] op_sel_hi:[1,0]
	v_add_f32_dpp v28, v28, v28 quad_perm:[2,3,0,1] row_mask:0xf bank_mask:0xf bound_ctrl:1
	v_pk_fma_f32 v[112:113], v[112:113], v[104:105], v[30:31]
	v_pk_mul_f32 v[30:31], v[98:99], v[120:121] op_sel_hi:[1,0]
	v_add_f32_dpp v28, v28, v28 row_half_mirror row_mask:0xf bank_mask:0xf bound_ctrl:1
	v_fmac_f32_e32 v28, v120, v121
	v_pk_fma_f32 v[114:115], v[114:115], v[106:107], v[30:31]
	v_cndmask_b32_e64 v121, v36, v28, s[52:53]
	s_waitcnt lgkmcnt(0)
	ds_read_b32 v124, v94 offset:7280
	ds_read_b32 v120, v93 offset:7152
	ds_read_b128 v[28:31], v92 offset:6912
	ds_read_b128 v[32:35], v92 offset:6896
	ds_read_b128 v[96:99], v92 offset:6656
	ds_read_b128 v[100:103], v92 offset:6640
	ds_read_b128 v[104:107], v92 offset:6400
	ds_read_b128 v[108:111], v92 offset:6384
	v_pk_mul_f32 v[6:7], v[118:119], v[6:7]
	s_nop 0
	v_pk_fma_f32 v[4:5], v[116:117], v[4:5], v[6:7]
	s_nop 0
	v_pk_fma_f32 v[0:1], v[112:113], v[0:1], v[4:5]
	s_nop 0
	v_pk_fma_f32 v[0:1], v[114:115], v[2:3], v[0:1]
	v_pk_mul_f32 v[2:3], v[12:13], v[122:123] op_sel_hi:[1,0]
	v_add_f32_e32 v0, v0, v1
	v_pk_fma_f32 v[116:117], v[116:117], v[20:21], v[2:3]
	v_pk_mul_f32 v[2:3], v[14:15], v[122:123] op_sel_hi:[1,0]
	v_add_f32_dpp v125, v0, v0 quad_perm:[1,0,3,2] row_mask:0xf bank_mask:0xf bound_ctrl:1
	v_pk_fma_f32 v[118:119], v[118:119], v[22:23], v[2:3]
	v_pk_mul_f32 v[2:3], v[8:9], v[122:123] op_sel_hi:[1,0]
	s_nop 0
	v_pk_fma_f32 v[112:113], v[112:113], v[16:17], v[2:3]
	v_pk_mul_f32 v[2:3], v[10:11], v[122:123] op_sel_hi:[1,0]
	s_nop 0
	v_pk_fma_f32 v[114:115], v[114:115], v[18:19], v[2:3]
	s_waitcnt lgkmcnt(0)
	ds_read_b32 v95, v94 offset:8192
	ds_read_b32 v36, v93 offset:8064
	ds_read_b128 v[12:15], v92 offset:7824
	ds_read_b128 v[20:23], v92 offset:7808
	ds_read_b128 v[0:3], v92 offset:7568
	ds_read_b128 v[8:11], v92 offset:7552
	ds_read_b128 v[4:7], v92 offset:7312
	ds_read_b128 v[16:19], v92 offset:7296
	v_add_f32_dpp v92, v125, v125 quad_perm:[2,3,0,1] row_mask:0xf bank_mask:0xf bound_ctrl:1
	s_nop 1
	v_add_f32_dpp v92, v92, v92 row_half_mirror row_mask:0xf bank_mask:0xf bound_ctrl:1
	v_fmac_f32_e32 v92, v122, v123
	v_cndmask_b32_e64 v94, v121, v92, s[54:55]
	v_pk_mul_f32 v[34:35], v[118:119], v[34:35]
	s_add_i32 s30, s30, 8
	v_pk_fma_f32 v[32:33], v[116:117], v[32:33], v[34:35]
	v_pk_mul_f32 v[34:35], v[98:99], v[120:121] op_sel_hi:[1,0]
	v_pk_fma_f32 v[28:29], v[112:113], v[28:29], v[32:33]
	v_pk_mul_f32 v[32:33], v[96:97], v[120:121] op_sel_hi:[1,0]
	v_pk_fma_f32 v[92:93], v[114:115], v[30:31], v[28:29]
	v_pk_mul_f32 v[28:29], v[100:101], v[120:121] op_sel_hi:[1,0]
	v_add_f32_e32 v92, v92, v93
	v_pk_mul_f32 v[30:31], v[102:103], v[120:121] op_sel_hi:[1,0]
	v_pk_fma_f32 v[28:29], v[116:117], v[108:109], v[28:29]
	v_add_f32_dpp v92, v92, v92 quad_perm:[1,0,3,2] row_mask:0xf bank_mask:0xf bound_ctrl:1
	v_pk_fma_f32 v[30:31], v[118:119], v[110:111], v[30:31]
	v_pk_fma_f32 v[32:33], v[112:113], v[104:105], v[32:33]
	v_add_f32_dpp v92, v92, v92 quad_perm:[2,3,0,1] row_mask:0xf bank_mask:0xf bound_ctrl:1
	v_pk_fma_f32 v[34:35], v[114:115], v[106:107], v[34:35]
	v_add_u32_e32 v93, 0, v91
	v_add_f32_dpp v92, v92, v92 row_half_mirror row_mask:0xf bank_mask:0xf bound_ctrl:1
	v_fmac_f32_e32 v92, v120, v124
	v_cndmask_b32_e64 v92, v94, v92, s[56:57]
	v_add_u32_e32 v89, 0x1c80, v89
	v_add_u32_e32 v90, 0x1c80, v90
	v_add_u32_e32 v88, 0x1c80, v88
	v_add_u32_e32 v91, 0x400, v91
	s_cmp_gt_u32 s30, 23
	s_waitcnt lgkmcnt(0)
	ds_write_b32 v93, v92
	s_cbranch_scc0 .LBB0_171
; template <int NW>
; __device__ void scan_gla(const P& p, int l, int b, int h, int dir, int part, LAS char* lds) {
;     ...
;     if (g + 1 < NCHK) GL_PREP(g + 1);
	s_add_i32 s30, s27, 1
	s_cmpk_lg_i32 s27, 0x87
	s_cbranch_scc0 .LBB0_206
	s_lshl_b32 s20, s30, 5
	s_and_b32 s20, s20, 32
	s_mulk_i32 s20, 0x390
	s_waitcnt vmcnt(0)
	v_lshlrev_b32_e32 v0, 16, v42
	v_mul_f32_e32 v2, 0x3e000000, v0
	v_add_u32_e32 v0, s20, v41
	v_lshlrev_b32_e32 v3, 16, v43
	v_lshl_add_u32 v1, v37, 2, v0
	v_mul_f32_e32 v2, v45, v2
	ds_write2st64_b32 v1, v45, v3 offset1:1
	ds_write_b32 v1, v2 offset:512
	v_lshlrev_b32_e32 v2, 16, v47
	v_mul_f32_e32 v2, 0x3e000000, v2
	v_lshlrev_b32_e32 v3, 16, v48
	v_add_u32_e32 v4, 0x90, v1
	v_mul_f32_e32 v2, v50, v2
	ds_write2st64_b32 v4, v50, v3 offset0:3 offset1:4
	ds_write_b32 v1, v2 offset:1424
	v_lshlrev_b32_e32 v2, 16, v52
	v_mul_f32_e32 v2, 0x3e000000, v2
	v_lshlrev_b32_e32 v3, 16, v53
	v_add_u32_e32 v4, 32, v1
	v_mul_f32_e32 v2, v55, v2
	ds_write2st64_b32 v4, v55, v3 offset0:7 offset1:8
	ds_write_b32 v1, v2 offset:2336
	v_lshlrev_b32_e32 v2, 16, v59
	v_mul_f32_e32 v2, 0x3e000000, v2
	v_lshlrev_b32_e32 v3, 16, v61
	v_add_u32_e32 v4, 0xb0, v1
	v_mul_f32_e32 v2, v68, v2
	ds_write2st64_b32 v4, v68, v3 offset0:10 offset1:11
	ds_write_b32 v1, v2 offset:3248
	v_lshlrev_b32_e32 v2, 16, v70
	v_mul_f32_e32 v2, 0x3e000000, v2
	v_lshlrev_b32_e32 v3, 16, v71
	v_add_u32_e32 v4, 64, v1
	v_mul_f32_e32 v2, v73, v2
	ds_write2st64_b32 v4, v73, v3 offset0:14 offset1:15
	ds_write_b32 v1, v2 offset:4160
	v_lshlrev_b32_e32 v2, 16, v75
	v_mul_f32_e32 v2, 0x3e000000, v2
	v_lshlrev_b32_e32 v3, 16, v76
	v_add_u32_e32 v4, 0xd0, v1
	v_mul_f32_e32 v2, v78, v2
	ds_write2st64_b32 v4, v78, v3 offset0:17 offset1:18
	ds_write_b32 v1, v2 offset:5072
	v_lshlrev_b32_e32 v2, 16, v80
	v_mul_f32_e32 v2, 0x3e000000, v2
	v_lshlrev_b32_e32 v3, 16, v81
	v_add_u32_e32 v4, 0x60, v1
	v_mul_f32_e32 v2, v83, v2
	ds_write2st64_b32 v4, v83, v3 offset0:21 offset1:22
	ds_write_b32 v1, v2 offset:5984
	v_lshlrev_b32_e32 v2, 16, v25
	v_mul_f32_e32 v2, 0x3e000000, v2
	v_lshlrev_b32_e32 v3, 16, v85
	v_add_u32_e32 v4, 0xf0, v1
	v_mul_f32_e32 v2, v86, v2
	ds_write2st64_b32 v4, v86, v3 offset0:24 offset1:25
	ds_write_b32 v1, v2 offset:6896
	s_and_saveexec_b64 s[36:37], s[38:39]
	v_lshlrev_b32_e32 v2, 16, v44
	ds_write_b32 v1, v2 offset:768
	v_lshlrev_b32_e32 v2, 16, v49
	ds_write_b32 v1, v2 offset:1680
	v_lshlrev_b32_e32 v2, 16, v54
	ds_write_b32 v1, v2 offset:2592
	v_lshlrev_b32_e32 v2, 16, v65
	ds_write_b32 v1, v2 offset:3504
	v_lshlrev_b32_e32 v2, 16, v72
	ds_write_b32 v1, v2 offset:4416
	v_lshlrev_b32_e32 v2, 16, v77
	ds_write_b32 v1, v2 offset:5328
	v_lshlrev_b32_e32 v2, 16, v82
	ds_write_b32 v1, v2 offset:6240
	v_lshlrev_b32_e32 v2, 16, v27
	ds_write_b32 v1, v2 offset:7152
	s_or_b64 exec, exec, s[36:37]
	s_and_saveexec_b64 s[36:37], s[40:41]
	ds_write_b32 v0, v46 offset:896
	ds_write_b32 v0, v51 offset:1808
	ds_write_b32 v0, v56 offset:2720
	ds_write_b32 v0, v69 offset:3632
	ds_write_b32 v0, v74 offset:4544
	ds_write_b32 v0, v79 offset:5456
	ds_write_b32 v0, v84 offset:6368
	ds_write_b32 v0, v87 offset:7280
	s_or_b64 exec, exec, s[36:37]
